# instruction selection: indexer relu as v_max_f32 (VOP2) instead of v_med3_f32 with an upper clamp
# speedup vs baseline: 1.0045x; 1.0045x over previous
; DI f32x16 mfma32(bf16x8 a, bf16x8 b, f32x16 c) { return __builtin_amdgcn_mfma_f32_32x32x16_bf16(a, b, c, 0, 0, 0); }
; DI u32 mono_key(float f) { u32 u = __float_as_uint(f); return (u & 0x80000000u) ? ~u : (u | 0x80000000u); }
; DI void dsa_item(const Params& p, int l, int tile32, int b, char* smem) {
;     ...
;       for (int t = 0; t < 4; ++t) {
;         const int key = (g * 4 + t) * 32 + c31;
;         f32x16 acc;
; #pragma unroll
;         for (int j = 0; j < 16; ++j) acc[j] = 0.f;
; #pragma unroll
;         for (int s = 0; s < 4; ++s) acc = mfma32(qa[s], kc[t][s], acc);
;         f32x2 ss2 = f32x2{0.f, 0.f};
; #pragma unroll
;         for (int hq = 0; hq < 8; ++hq) {
;           const f32x2 rr = f32x2{__builtin_amdgcn_fmed3f(acc[2 * hq], 0.f, 3.0e38f), __builtin_amdgcn_fmed3f(acc[2 * hq + 1], 0.f, 3.0e38f)};
;           ss2 = __builtin_elementwise_fma(wq2[hq], rr, ss2);
;         }
;         const float s0 = ss2.x, s1 = ss2.y;
;         const u32 k0 = mono_key(s0), k1 = mono_key(s1);
;         const bool c0 = (key <= qpos0) && (k0 > tauA), c1 = (key <= qpos0 + 1) && (k1 > tauB);
;         const u64 m0 = __ballot(c0), m1 = __ballot(c1);
;         if (m0 | m1) {
;           const u32 h0 = hh ? (u32)(m0 >> 32) : (u32)m0, h1 = hh ? (u32)(m1 >> 32) : (u32)m1;
;           const int pA = (hh ? cnt2 : cnt0) + __popc(h0 & lmask), pB = (hh ? cnt3 : cnt1) + __popc(h1 & lmask);
;           if (c0) { ckey[(2 * hh) * DCAP + pA] = k0; cidx[(2 * hh) * DCAP + pA] = (u16)key; }
;           if (c1) { ckey[(2 * hh + 1) * DCAP + pB] = k1; cidx[(2 * hh + 1) * DCAP + pB] = (u16)key; }
;           cnt0 += __popc((u32)m0); cnt2 += __popc((u32)(m0 >> 32));
;           cnt1 += __popc((u32)m1); cnt3 += __popc((u32)(m1 >> 32));
;         }
.LBB0_499:
	s_or_b64 exec, exec, s[2:3]
	v_mfma_f32_32x32x16_bf16 v[2:17], v[18:21], v[2:5], 0
	v_cndmask_b32_e32 v0, v223, v224, vcc
	v_mfma_f32_32x32x16_bf16 v[2:17], v[22:25], v[98:101], v[2:17]
	v_mfma_f32_32x32x16_bf16 v[2:17], v[26:29], v[94:97], v[2:17]
	v_lshl_or_b32 v95, s54, 7, v192
	v_cndmask_b32_e32 v94, v221, v222, vcc
	v_cmp_le_i32_e64 s[0:1], v95, v217
	v_cmp_le_i32_e64 s[2:3], v95, v219
	v_mfma_f32_32x32x16_bf16 v[2:17], v[30:33], v[90:93], v[2:17]
	s_nop 11
	v_max_f32_e32 v2, 0, v2
	v_max_f32_e32 v3, 0, v3
	v_max_f32_e32 v4, 0, v4
	v_max_f32_e32 v5, 0, v5
	v_fma_f32 v2, v178, v2, 0
	v_fma_f32 v3, v179, v3, 0
	v_max_f32_e32 v6, 0, v6
	v_max_f32_e32 v7, 0, v7
	v_fmac_f32_e32 v2, v38, v4
	v_fmac_f32_e32 v3, v39, v5
	v_max_f32_e32 v8, 0, v8
	v_max_f32_e32 v9, 0, v9
	v_fmac_f32_e32 v2, v180, v6
	v_fmac_f32_e32 v3, v181, v7
	v_max_f32_e32 v10, 0, v10
	v_max_f32_e32 v11, 0, v11
	v_fmac_f32_e32 v2, v40, v8
	v_fmac_f32_e32 v3, v41, v9
	v_max_f32_e32 v12, 0, v12
	v_max_f32_e32 v13, 0, v13
	v_fmac_f32_e32 v2, v182, v10
	v_fmac_f32_e32 v3, v183, v11
	v_max_f32_e32 v14, 0, v14
	v_max_f32_e32 v15, 0, v15
	v_fmac_f32_e32 v2, v34, v12
	v_fmac_f32_e32 v3, v35, v13
	v_max_f32_e32 v16, 0, v16
	v_max_f32_e32 v17, 0, v17
	v_fmac_f32_e32 v2, v184, v14
	v_fmac_f32_e32 v3, v185, v15
	v_fma_f32 v4, v36, v16, v2
	v_fma_f32 v5, v37, v17, v3
	v_ashrrev_i32_e32 v2, 31, v4
	v_ashrrev_i32_e32 v6, 31, v5
	v_or_b32_e32 v2, 0x80000000, v2
	v_or_b32_e32 v6, 0x80000000, v6
	v_xor_b32_e32 v3, v4, v2
	v_xor_b32_e32 v2, v5, v6
	v_cmp_gt_u32_e64 s[4:5], v3, v0
	v_cmp_gt_u32_e64 s[6:7], v2, v94
	s_and_b64 s[10:11], s[0:1], s[4:5]
	s_and_b64 s[4:5], s[2:3], s[6:7]
	s_or_b64 s[6:7], s[10:11], s[4:5]
	s_cbranch_scc0 .LBB0_505
	s_and_b64 s[0:1], s[10:11], exec
	s_and_b64 s[2:3], s[4:5], exec
	s_and_saveexec_b64 s[6:7], s[10:11]
	s_cbranch_execz .LBB0_502
	v_mov_b32_e32 v4, s1
	v_mov_b32_e32 v5, s0
	v_cndmask_b32_e32 v4, v4, v5, vcc
	v_and_b32_e32 v4, v4, v218
	v_bcnt_u32_b32 v4, v4, 0
	v_cndmask_b32_e32 v5, v187, v173, vcc
	v_add3_u32 v4, v5, v214, v4
	v_lshl_add_u32 v5, v4, 2, v190
	ds_write_b32 v5, v3
	v_lshlrev_b32_e32 v3, 1, v4
	v_sub_u32_e32 v3, v5, v3
	ds_write_b16 v3, v95 offset:10240

; DI f32x16 mfma32(bf16x8 a, bf16x8 b, f32x16 c) { return __builtin_amdgcn_mfma_f32_32x32x16_bf16(a, b, c, 0, 0, 0); }
; DI u32 mono_key(float f) { u32 u = __float_as_uint(f); return (u & 0x80000000u) ? ~u : (u | 0x80000000u); }
; DI void dsa_item(const Params& p, int l, int tile32, int b, char* smem) {
;     ...
;       for (int t = 0; t < 4; ++t) {
;         const int key = (g * 4 + t) * 32 + c31;
;         f32x16 acc;
; #pragma unroll
;         for (int j = 0; j < 16; ++j) acc[j] = 0.f;
; #pragma unroll
;         for (int s = 0; s < 4; ++s) acc = mfma32(qa[s], kc[t][s], acc);
;         f32x2 ss2 = f32x2{0.f, 0.f};
; #pragma unroll
;         for (int hq = 0; hq < 8; ++hq) {
;           const f32x2 rr = f32x2{__builtin_amdgcn_fmed3f(acc[2 * hq], 0.f, 3.0e38f), __builtin_amdgcn_fmed3f(acc[2 * hq + 1], 0.f, 3.0e38f)};
;           ss2 = __builtin_elementwise_fma(wq2[hq], rr, ss2);
;         }
;         const float s0 = ss2.x, s1 = ss2.y;
;         const u32 k0 = mono_key(s0), k1 = mono_key(s1);
;         const bool c0 = (key <= qpos0) && (k0 > tauA), c1 = (key <= qpos0 + 1) && (k1 > tauB);
;         const u64 m0 = __ballot(c0), m1 = __ballot(c1);
;         if (m0 | m1) {
;           const u32 h0 = hh ? (u32)(m0 >> 32) : (u32)m0, h1 = hh ? (u32)(m1 >> 32) : (u32)m1;
;           const int pA = (hh ? cnt2 : cnt0) + __popc(h0 & lmask), pB = (hh ? cnt3 : cnt1) + __popc(h1 & lmask);
;           if (c0) { ckey[(2 * hh) * DCAP + pA] = k0; cidx[(2 * hh) * DCAP + pA] = (u16)key; }
;           if (c1) { ckey[(2 * hh + 1) * DCAP + pB] = k1; cidx[(2 * hh + 1) * DCAP + pB] = (u16)key; }
;           cnt0 += __popc((u32)m0); cnt2 += __popc((u32)(m0 >> 32));
;           cnt1 += __popc((u32)m1); cnt3 += __popc((u32)(m1 >> 32));
;         }
.LBB0_505:
	v_mfma_f32_32x32x16_bf16 v[2:17], v[18:21], v[86:89], 0
	v_mfma_f32_32x32x16_bf16 v[2:17], v[22:25], v[82:85], v[2:17]
	v_mfma_f32_32x32x16_bf16 v[2:17], v[26:29], v[78:81], v[2:17]
	v_or_b32_e32 v78, 32, v95
	v_cmp_le_i32_e64 s[0:1], v78, v217
	v_cmp_le_i32_e64 s[2:3], v78, v219
	v_mfma_f32_32x32x16_bf16 v[2:17], v[30:33], v[74:77], v[2:17]
	s_nop 11
	v_max_f32_e32 v2, 0, v2
	v_max_f32_e32 v3, 0, v3
	v_max_f32_e32 v4, 0, v4
	v_max_f32_e32 v5, 0, v5
	v_fma_f32 v2, v178, v2, 0
	v_fma_f32 v3, v179, v3, 0
	v_max_f32_e32 v6, 0, v6
	v_max_f32_e32 v7, 0, v7
	v_fmac_f32_e32 v2, v38, v4
	v_fmac_f32_e32 v3, v39, v5
	v_max_f32_e32 v8, 0, v8
	v_max_f32_e32 v9, 0, v9
	v_fmac_f32_e32 v2, v180, v6
	v_fmac_f32_e32 v3, v181, v7
	v_max_f32_e32 v10, 0, v10
	v_max_f32_e32 v11, 0, v11
	v_fmac_f32_e32 v2, v40, v8
	v_fmac_f32_e32 v3, v41, v9
	v_max_f32_e32 v12, 0, v12
	v_max_f32_e32 v13, 0, v13
	v_fmac_f32_e32 v2, v182, v10
	v_fmac_f32_e32 v3, v183, v11
	v_max_f32_e32 v14, 0, v14
	v_max_f32_e32 v15, 0, v15
	v_fmac_f32_e32 v2, v34, v12
	v_fmac_f32_e32 v3, v35, v13
	v_max_f32_e32 v16, 0, v16
	v_max_f32_e32 v17, 0, v17
	v_fmac_f32_e32 v2, v184, v14
	v_fmac_f32_e32 v3, v185, v15
	v_fma_f32 v4, v36, v16, v2
	v_fma_f32 v5, v37, v17, v3
	v_ashrrev_i32_e32 v2, 31, v4
	v_ashrrev_i32_e32 v6, 31, v5
	v_or_b32_e32 v2, 0x80000000, v2
	v_or_b32_e32 v6, 0x80000000, v6
	v_xor_b32_e32 v3, v4, v2
	v_xor_b32_e32 v2, v5, v6
	v_cmp_gt_u32_e64 s[4:5], v3, v0
	v_cmp_gt_u32_e64 s[6:7], v2, v94
	s_and_b64 s[10:11], s[0:1], s[4:5]
	s_and_b64 s[4:5], s[2:3], s[6:7]
	s_or_b64 s[6:7], s[10:11], s[4:5]
	s_cbranch_scc0 .LBB0_511
	s_and_b64 s[2:3], s[10:11], exec
	s_and_b64 s[0:1], s[4:5], exec
	s_and_saveexec_b64 s[6:7], s[10:11]
	s_cbranch_execz .LBB0_508
	v_mov_b32_e32 v4, s3
	v_mov_b32_e32 v5, s2
	v_cndmask_b32_e32 v4, v4, v5, vcc
	v_and_b32_e32 v4, v4, v218
	v_bcnt_u32_b32 v4, v4, 0
	v_cndmask_b32_e32 v5, v187, v173, vcc
	v_add3_u32 v4, v5, v214, v4
	v_lshl_add_u32 v5, v4, 2, v190
	ds_write_b32 v5, v3
	v_lshlrev_b32_e32 v3, 1, v4
	v_sub_u32_e32 v3, v5, v3
	ds_write_b16 v3, v78 offset:10240

; DI f32x16 mfma32(bf16x8 a, bf16x8 b, f32x16 c) { return __builtin_amdgcn_mfma_f32_32x32x16_bf16(a, b, c, 0, 0, 0); }
; DI u32 mono_key(float f) { u32 u = __float_as_uint(f); return (u & 0x80000000u) ? ~u : (u | 0x80000000u); }
; DI void dsa_item(const Params& p, int l, int tile32, int b, char* smem) {
;     ...
;       for (int t = 0; t < 4; ++t) {
;         const int key = (g * 4 + t) * 32 + c31;
;         f32x16 acc;
; #pragma unroll
;         for (int j = 0; j < 16; ++j) acc[j] = 0.f;
; #pragma unroll
;         for (int s = 0; s < 4; ++s) acc = mfma32(qa[s], kc[t][s], acc);
;         f32x2 ss2 = f32x2{0.f, 0.f};
; #pragma unroll
;         for (int hq = 0; hq < 8; ++hq) {
;           const f32x2 rr = f32x2{__builtin_amdgcn_fmed3f(acc[2 * hq], 0.f, 3.0e38f), __builtin_amdgcn_fmed3f(acc[2 * hq + 1], 0.f, 3.0e38f)};
;           ss2 = __builtin_elementwise_fma(wq2[hq], rr, ss2);
;         }
;         const float s0 = ss2.x, s1 = ss2.y;
;         const u32 k0 = mono_key(s0), k1 = mono_key(s1);
;         const bool c0 = (key <= qpos0) && (k0 > tauA), c1 = (key <= qpos0 + 1) && (k1 > tauB);
;         const u64 m0 = __ballot(c0), m1 = __ballot(c1);
;         if (m0 | m1) {
;           const u32 h0 = hh ? (u32)(m0 >> 32) : (u32)m0, h1 = hh ? (u32)(m1 >> 32) : (u32)m1;
;           const int pA = (hh ? cnt2 : cnt0) + __popc(h0 & lmask), pB = (hh ? cnt3 : cnt1) + __popc(h1 & lmask);
;           if (c0) { ckey[(2 * hh) * DCAP + pA] = k0; cidx[(2 * hh) * DCAP + pA] = (u16)key; }
;           if (c1) { ckey[(2 * hh + 1) * DCAP + pB] = k1; cidx[(2 * hh + 1) * DCAP + pB] = (u16)key; }
;           cnt0 += __popc((u32)m0); cnt2 += __popc((u32)(m0 >> 32));
;           cnt1 += __popc((u32)m1); cnt3 += __popc((u32)(m1 >> 32));
;         }
.LBB0_511:
	v_mfma_f32_32x32x16_bf16 v[2:17], v[18:21], v[70:73], 0
	v_mfma_f32_32x32x16_bf16 v[2:17], v[22:25], v[66:69], v[2:17]
	v_mfma_f32_32x32x16_bf16 v[2:17], v[26:29], v[62:65], v[2:17]
	v_or_b32_e32 v62, 64, v95
	v_cmp_le_i32_e64 s[0:1], v62, v217
	v_cmp_le_i32_e64 s[2:3], v62, v219
	v_mfma_f32_32x32x16_bf16 v[2:17], v[30:33], v[58:61], v[2:17]
	s_nop 11
	v_max_f32_e32 v2, 0, v2
	v_max_f32_e32 v3, 0, v3
	v_max_f32_e32 v4, 0, v4
	v_max_f32_e32 v5, 0, v5
	v_fma_f32 v2, v178, v2, 0
	v_fma_f32 v3, v179, v3, 0
	v_max_f32_e32 v6, 0, v6
	v_max_f32_e32 v7, 0, v7
	v_fmac_f32_e32 v2, v38, v4
	v_fmac_f32_e32 v3, v39, v5
	v_max_f32_e32 v8, 0, v8
	v_max_f32_e32 v9, 0, v9
	v_fmac_f32_e32 v2, v180, v6
	v_fmac_f32_e32 v3, v181, v7
	v_max_f32_e32 v10, 0, v10
	v_max_f32_e32 v11, 0, v11
	v_fmac_f32_e32 v2, v40, v8
	v_fmac_f32_e32 v3, v41, v9
	v_max_f32_e32 v12, 0, v12
	v_max_f32_e32 v13, 0, v13
	v_fmac_f32_e32 v2, v182, v10
	v_fmac_f32_e32 v3, v183, v11
	v_max_f32_e32 v14, 0, v14
	v_max_f32_e32 v15, 0, v15
	v_fmac_f32_e32 v2, v34, v12
	v_fmac_f32_e32 v3, v35, v13
	v_max_f32_e32 v16, 0, v16
	v_max_f32_e32 v17, 0, v17
	v_fmac_f32_e32 v2, v184, v14
	v_fmac_f32_e32 v3, v185, v15
	v_fma_f32 v4, v36, v16, v2
	v_fma_f32 v5, v37, v17, v3
	v_ashrrev_i32_e32 v2, 31, v4
	v_ashrrev_i32_e32 v6, 31, v5
	v_or_b32_e32 v2, 0x80000000, v2
	v_or_b32_e32 v6, 0x80000000, v6
	v_xor_b32_e32 v3, v4, v2
	v_xor_b32_e32 v2, v5, v6
	v_cmp_gt_u32_e64 s[4:5], v3, v0
	v_cmp_gt_u32_e64 s[6:7], v2, v94
	s_and_b64 s[10:11], s[0:1], s[4:5]
	s_and_b64 s[4:5], s[2:3], s[6:7]
	s_or_b64 s[6:7], s[10:11], s[4:5]
	s_cbranch_scc0 .LBB0_517
	s_and_b64 s[2:3], s[10:11], exec
	s_and_b64 s[0:1], s[4:5], exec
	s_and_saveexec_b64 s[6:7], s[10:11]
	s_cbranch_execz .LBB0_514
	v_mov_b32_e32 v4, s3
	v_mov_b32_e32 v5, s2
	v_cndmask_b32_e32 v4, v4, v5, vcc
	v_and_b32_e32 v4, v4, v218
	v_bcnt_u32_b32 v4, v4, 0
	v_cndmask_b32_e32 v5, v187, v173, vcc
	v_add3_u32 v4, v5, v214, v4
	v_lshl_add_u32 v5, v4, 2, v190
	ds_write_b32 v5, v3
	v_lshlrev_b32_e32 v3, 1, v4
	v_sub_u32_e32 v3, v5, v3
	ds_write_b16 v3, v62 offset:10240

; DI f32x16 mfma32(bf16x8 a, bf16x8 b, f32x16 c) { return __builtin_amdgcn_mfma_f32_32x32x16_bf16(a, b, c, 0, 0, 0); }
; DI u32 mono_key(float f) { u32 u = __float_as_uint(f); return (u & 0x80000000u) ? ~u : (u | 0x80000000u); }
; DI void dsa_item(const Params& p, int l, int tile32, int b, char* smem) {
;     ...
;       for (int t = 0; t < 4; ++t) {
;         const int key = (g * 4 + t) * 32 + c31;
;         f32x16 acc;
; #pragma unroll
;         for (int j = 0; j < 16; ++j) acc[j] = 0.f;
; #pragma unroll
;         for (int s = 0; s < 4; ++s) acc = mfma32(qa[s], kc[t][s], acc);
;         f32x2 ss2 = f32x2{0.f, 0.f};
; #pragma unroll
;         for (int hq = 0; hq < 8; ++hq) {
;           const f32x2 rr = f32x2{__builtin_amdgcn_fmed3f(acc[2 * hq], 0.f, 3.0e38f), __builtin_amdgcn_fmed3f(acc[2 * hq + 1], 0.f, 3.0e38f)};
;           ss2 = __builtin_elementwise_fma(wq2[hq], rr, ss2);
;         }
;         const float s0 = ss2.x, s1 = ss2.y;
;         const u32 k0 = mono_key(s0), k1 = mono_key(s1);
;         const bool c0 = (key <= qpos0) && (k0 > tauA), c1 = (key <= qpos0 + 1) && (k1 > tauB);
;         const u64 m0 = __ballot(c0), m1 = __ballot(c1);
;         if (m0 | m1) {
;           const u32 h0 = hh ? (u32)(m0 >> 32) : (u32)m0, h1 = hh ? (u32)(m1 >> 32) : (u32)m1;
;           const int pA = (hh ? cnt2 : cnt0) + __popc(h0 & lmask), pB = (hh ? cnt3 : cnt1) + __popc(h1 & lmask);
;           if (c0) { ckey[(2 * hh) * DCAP + pA] = k0; cidx[(2 * hh) * DCAP + pA] = (u16)key; }
;           if (c1) { ckey[(2 * hh + 1) * DCAP + pB] = k1; cidx[(2 * hh + 1) * DCAP + pB] = (u16)key; }
;           cnt0 += __popc((u32)m0); cnt2 += __popc((u32)(m0 >> 32));
;           cnt1 += __popc((u32)m1); cnt3 += __popc((u32)(m1 >> 32));
;         }
.LBB0_517:
	v_mfma_f32_32x32x16_bf16 v[2:17], v[18:21], v[54:57], 0
	v_mfma_f32_32x32x16_bf16 v[2:17], v[22:25], v[50:53], v[2:17]
	v_mfma_f32_32x32x16_bf16 v[2:17], v[26:29], v[46:49], v[2:17]
	v_or_b32_e32 v46, 0x60, v95
	v_cmp_le_i32_e64 s[0:1], v46, v217
	v_cmp_le_i32_e64 s[2:3], v46, v219
	v_mfma_f32_32x32x16_bf16 v[2:17], v[30:33], v[42:45], v[2:17]
	s_nop 11
	v_max_f32_e32 v2, 0, v2
	v_max_f32_e32 v3, 0, v3
	v_max_f32_e32 v4, 0, v4
	v_max_f32_e32 v5, 0, v5
	v_fma_f32 v2, v178, v2, 0
	v_fma_f32 v3, v179, v3, 0
	v_max_f32_e32 v6, 0, v6
	v_max_f32_e32 v7, 0, v7
	v_fmac_f32_e32 v2, v38, v4
	v_fmac_f32_e32 v3, v39, v5
	v_max_f32_e32 v8, 0, v8
	v_max_f32_e32 v9, 0, v9
	v_fmac_f32_e32 v2, v180, v6
	v_fmac_f32_e32 v3, v181, v7
	v_max_f32_e32 v10, 0, v10
	v_max_f32_e32 v11, 0, v11
	v_fmac_f32_e32 v2, v40, v8
	v_fmac_f32_e32 v3, v41, v9
	v_max_f32_e32 v12, 0, v12
	v_max_f32_e32 v13, 0, v13
	v_fmac_f32_e32 v2, v182, v10
	v_fmac_f32_e32 v3, v183, v11
	v_max_f32_e32 v14, 0, v14
	v_max_f32_e32 v15, 0, v15
	v_fmac_f32_e32 v2, v34, v12
	v_fmac_f32_e32 v3, v35, v13
	v_max_f32_e32 v16, 0, v16
	v_max_f32_e32 v17, 0, v17
	v_fmac_f32_e32 v2, v184, v14
	v_fmac_f32_e32 v3, v185, v15
	v_fma_f32 v4, v36, v16, v2
	v_fma_f32 v5, v37, v17, v3
	v_ashrrev_i32_e32 v2, 31, v4
	v_ashrrev_i32_e32 v6, 31, v5
	v_or_b32_e32 v2, 0x80000000, v2
	v_or_b32_e32 v6, 0x80000000, v6
	v_xor_b32_e32 v3, v4, v2
	v_xor_b32_e32 v2, v5, v6
	v_cmp_gt_u32_e64 s[4:5], v3, v0
	v_cmp_gt_u32_e64 s[6:7], v2, v94
	s_and_b64 s[10:11], s[0:1], s[4:5]
	s_and_b64 s[4:5], s[2:3], s[6:7]
	s_or_b64 s[6:7], s[10:11], s[4:5]
	s_cbranch_scc0 .LBB0_374
	s_and_b64 s[2:3], s[10:11], exec
	s_and_b64 s[0:1], s[4:5], exec
	s_and_saveexec_b64 s[6:7], s[10:11]
	s_cbranch_execz .LBB0_520
	v_mov_b32_e32 v0, s3
	v_mov_b32_e32 v4, s2
	v_cndmask_b32_e32 v0, v0, v4, vcc
	v_and_b32_e32 v0, v0, v218
	v_bcnt_u32_b32 v0, v0, 0
	v_cndmask_b32_e32 v4, v187, v173, vcc
	v_add3_u32 v0, v4, v214, v0
	v_lshl_add_u32 v4, v0, 2, v190
	v_lshlrev_b32_e32 v0, 1, v0
	v_sub_u32_e32 v0, v4, v0
	ds_write_b32 v4, v3
	ds_write_b16 v0, v46 offset:10240
